# S16 plus 5 of the 8 attention-epilogue gate loads issued at the top of the last masked iteration (into the idle K staging registers and v244-251), epilogue vmcnt re-derived
# speedup vs baseline: 1.0076x; 1.0046x over previous
; __device__ __forceinline__ unsigned cvt_pk_bf16(float lo, float hi) { unsigned r; asm volatile("v_cvt_pk_bf16_f32 %0, %1, %2" : "=v"(r) : "v"(lo), "v"(hi)); return r; }
; __device__ __forceinline__ float bf_lo(unsigned w) { return __uint_as_float(w << 16); }
; __device__ __forceinline__ float bf_hi(unsigned w) { return __uint_as_float(w & 0xffff0000u); }
; __device__ __forceinline__ void unit(LAS unsigned char* lds, int b, int h, int qb, const bf16_t* Q, const bf16_t* Kn, const bf16_t* Kr, const bf16_t* VT, const bf16_t* proj, bf16_t* ymix, int wv) {
;     ...
;     lrun += shfl_xor_f(lrun, 32);
;     const float inv = 1.f / lrun;
;     const size_t tok = (size_t)tok0 + qidx;
;     u32x2 gts[4][4];
; #pragma unroll
;     for (int blk = 0; blk < 4; ++blk)
; #pragma unroll
;         for (int g = 0; g < 4; ++g) gts[blk][g] = *(const u32x2*)(proj + tok * NIN + PJ_BG + h * 128 + 32 * blk + 8 * g + 4 * hi);
; #pragma unroll
;     for (int blk = 0; blk < 4; ++blk)
; #pragma unroll
;         for (int g = 0; g < 4; ++g) { const int dv = 32 * blk + 8 * g + 4 * hi; const u32x2 gt = gts[blk][g];
;             u32x2 w; w.x = cvt_pk_bf16(o[blk][4 * g + 0] * inv * bf_lo(gt.x), o[blk][4 * g + 1] * inv * bf_hi(gt.x)); w.y = cvt_pk_bf16(o[blk][4 * g + 2] * inv * bf_lo(gt.y), o[blk][4 * g + 3] * inv * bf_hi(gt.y));
;             *(u32x2*)(ymix + tok * DM + 512 + h * 128 + dv) = w; }
.LBB0_605:
	s_add_i32 s8, s71, 0
	s_add_i32 s8, s8, 0x12c00
	v_add3_u32 v0, s8, v227, v226
	ds_read2_b64 v[2:5], v0 offset1:2
	v_ashrrev_i32_e32 v217, 31, v216
	v_mov_b64_e32 v[6:7], s[22:23]
	v_lshl_add_u64 v[120:121], v[216:217], 0, s[54:55]
	v_mad_u64_u32 v[122:123], s[8:9], v120, s66, v[6:7]
	ds_read2_b64 v[6:9], v0 offset0:4 offset1:6
	ds_read2_b64 v[12:15], v0 offset0:8 offset1:10
	v_add_u32_e32 v88, 0x1000, v0
	v_add_u32_e32 v104, 0x2000, v0
	s_waitcnt lgkmcnt(2)
	v_mfma_f32_32x32x16_bf16 v[64:79], v[2:5], v[200:203], v[64:79]
	ds_read2_b64 v[2:5], v0 offset0:12 offset1:14
	v_add_u32_e32 v0, 0x3000, v0
	v_mad_i32_i24 v123, v121, s66, v123
	s_lshl_b32 s12, s69, 1
	ds_read2_b64 v[80:83], v88 offset0:32 offset1:34
	ds_read2_b64 v[84:87], v88 offset0:36 offset1:38
	v_mov_b32_e32 v11, v222
	s_add_i32 s68, s68, s31
	s_waitcnt lgkmcnt(4)
	v_mfma_f32_32x32x16_bf16 v[64:79], v[6:9], v[196:199], v[64:79]
	ds_read2_b64 v[6:9], v88 offset0:40 offset1:42
	ds_read2_b64 v[88:91], v88 offset0:44 offset1:46
	ds_read2_b64 v[92:95], v104 offset0:64 offset1:66
	ds_read2_b64 v[96:99], v104 offset0:68 offset1:70
	ds_read2_b64 v[100:103], v104 offset0:72 offset1:74
	ds_read2_b64 v[104:107], v104 offset0:76 offset1:78
	ds_read2_b64 v[108:111], v0 offset0:96 offset1:98
	s_cmpk_lt_i32 s68, 0x400
	s_waitcnt lgkmcnt(10)
	v_mfma_f32_32x32x16_bf16 v[64:79], v[12:15], v[192:195], v[64:79]
	ds_read2_b64 v[12:15], v0 offset0:100 offset1:102
	ds_read2_b64 v[112:115], v0 offset0:104 offset1:106
	ds_read2_b64 v[116:119], v0 offset0:108 offset1:110
	v_lshlrev_b32_e32 v0, 1, v225
	s_waitcnt lgkmcnt(0)
	s_barrier
	v_mfma_f32_32x32x16_bf16 v[64:79], v[2:5], v[180:183], v[64:79]
	v_lshl_add_u64 v[2:3], v[122:123], 0, s[12:13]
	v_lshl_add_u64 v[2:3], v[2:3], 0, v[0:1]
	v_add_co_u32_e32 v4, vcc, s67, v2
	s_nop 1
	v_addc_co_u32_e32 v5, vcc, 0, v3, vcc
	v_and_b32_e32 v168, 32, v222
	v_lshrrev_b32_e32 v168, 2, v168
	v_mov_b32_e32 v169, 0
	v_lshl_add_u64 v[168:169], v[4:5], 0, v[168:169]
	v_lshl_add_u64 v[2:3], v[2:3], 0, s[16:17]
	v_mfma_f32_32x32x16_bf16 v[48:63], v[80:83], v[200:203], v[48:63]
	v_lshlrev_b32_e32 v4, 2, v11
	v_xor_b32_e32 v4, 0x80, v4
	ds_bpermute_b32 v4, v4, v10
	v_mfma_f32_32x32x16_bf16 v[48:63], v[84:87], v[196:199], v[48:63]
	v_mfma_f32_32x32x16_bf16 v[48:63], v[6:9], v[192:195], v[48:63]
	s_waitcnt lgkmcnt(0)
	v_add_f32_e32 v6, v10, v4
	v_div_scale_f32 v7, s[8:9], v6, v6, 1.0
	v_rcp_f32_e32 v134, v7
	v_mfma_f32_32x32x16_bf16 v[48:63], v[88:91], v[180:183], v[48:63]
	global_load_dwordx4 v[156:159], v[168:169], off offset:160
	global_load_dwordx4 v[160:163], v[168:169], off offset:192
	global_load_dwordx4 v[164:167], v[168:169], off offset:224
	s_nop 0
	v_mfma_f32_32x32x16_bf16 v[32:47], v[92:95], v[200:203], v[32:47]
	v_fma_f32 v92, -v7, v134, 1.0
	v_fmac_f32_e32 v134, v92, v134
	v_div_scale_f32 v92, vcc, 1.0, v6, 1.0
	v_mul_f32_e32 v93, v92, v134
	v_fma_f32 v94, -v7, v93, v92
	v_fmac_f32_e32 v93, v94, v134
	v_fma_f32 v7, -v7, v93, v92
	v_mfma_f32_32x32x16_bf16 v[16:31], v[108:111], v[200:203], v[16:31]
	v_div_fmas_f32 v7, v7, v134, v93
	v_div_fixup_f32 v92, v7, v6, 1.0
	v_mul_f32_e32 v64, v64, v92
	v_lshlrev_b64 v[6:7], 12, v[120:121]
	v_mul_f32_e32 v65, v65, v92
	v_lshl_add_u64 v[6:7], s[46:47], 0, v[6:7]
	v_lshl_add_u64 v[6:7], v[6:7], 0, s[12:13]
	v_lshl_add_u64 v[6:7], v[6:7], 0, v[0:1]
	v_mul_f32_e32 v0, v68, v92
	v_mfma_f32_32x32x16_bf16 v[16:31], v[12:15], v[196:199], v[16:31]
	v_mul_f32_e32 v12, v69, v92
	s_waitcnt vmcnt(3)
	v_permlane32_swap_b32_e32 v176, v178
	v_permlane32_swap_b32_e32 v177, v179
	v_lshlrev_b32_e32 v93, 16, v176
	v_mul_f32_e32 v64, v64, v93
	v_and_b32_e32 v93, 0xffff0000, v176
	v_mul_f32_e32 v65, v65, v93
	v_cvt_pk_bf16_f32 v136, v64, v65
	v_mul_f32_e32 v65, v66, v92
	v_lshlrev_b32_e32 v66, 16, v177
	v_mul_f32_e32 v65, v65, v66
	v_mul_f32_e32 v66, v67, v92
	v_and_b32_e32 v67, 0xffff0000, v177
	v_mul_f32_e32 v66, v66, v67
	v_cvt_pk_bf16_f32 v137, v65, v66
	v_and_b32_e32 v252, 32, v222
	v_lshrrev_b32_e32 v252, 2, v252
	v_mov_b32_e32 v253, 0
	v_lshl_add_u64 v[252:253], v[6:7], 0, v[252:253]
	s_waitcnt vmcnt(3)
	v_lshlrev_b32_e32 v64, 16, v178
	v_and_b32_e32 v13, 0xffff0000, v178
	v_mul_f32_e32 v0, v0, v64
	v_mul_f32_e32 v12, v12, v13
	v_cvt_pk_bf16_f32 v138, v0, v12
	v_mul_f32_e32 v0, v70, v92
	v_lshlrev_b32_e32 v13, 16, v179
	v_mul_f32_e32 v0, v0, v13
	v_mul_f32_e32 v13, v71, v92
	v_and_b32_e32 v14, 0xffff0000, v179
	v_mul_f32_e32 v13, v13, v14
	v_cvt_pk_bf16_f32 v139, v0, v13
	s_nop 1
	v_permlane32_swap_b32_e32 v136, v138
	v_permlane32_swap_b32_e32 v137, v139
	global_store_dwordx4 v[252:253], v[136:139], off offset:1024
	v_mul_f32_e32 v0, v72, v92
	s_waitcnt vmcnt(4)
	v_permlane32_swap_b32_e32 v184, v186
	v_permlane32_swap_b32_e32 v185, v187
	v_lshlrev_b32_e32 v12, 16, v184
	v_mul_f32_e32 v0, v0, v12
	v_mul_f32_e32 v12, v73, v92
	v_and_b32_e32 v13, 0xffff0000, v184
	v_mul_f32_e32 v12, v12, v13
	v_cvt_pk_bf16_f32 v140, v0, v12
	v_mul_f32_e32 v0, v74, v92
	v_lshlrev_b32_e32 v13, 16, v185
	v_mul_f32_e32 v0, v0, v13
	v_mul_f32_e32 v13, v75, v92
	v_and_b32_e32 v14, 0xffff0000, v185
	v_mul_f32_e32 v13, v13, v14
	v_cvt_pk_bf16_f32 v141, v0, v13
	v_mul_f32_e32 v0, v76, v92
	s_waitcnt vmcnt(4)
	v_lshlrev_b32_e32 v12, 16, v186
	v_mul_f32_e32 v0, v0, v12
	v_mul_f32_e32 v12, v77, v92
	v_and_b32_e32 v10, 0xffff0000, v186
	v_mul_f32_e32 v10, v12, v10
	v_cvt_pk_bf16_f32 v142, v0, v10
	v_mul_f32_e32 v0, v78, v92
	v_lshlrev_b32_e32 v12, 16, v187
	v_mul_f32_e32 v0, v0, v12
	v_mul_f32_e32 v12, v79, v92
	v_and_b32_e32 v11, 0xffff0000, v187
	v_mul_f32_e32 v11, v12, v11
	v_mfma_f32_32x32x16_bf16 v[32:47], v[96:99], v[196:199], v[32:47]
	v_cvt_pk_bf16_f32 v143, v0, v11
	s_nop 1
	v_permlane32_swap_b32_e32 v140, v142
	v_permlane32_swap_b32_e32 v141, v143
	global_store_dwordx4 v[252:253], v[140:143], off offset:1056
	v_mul_f32_e32 v0, v48, v92
	s_waitcnt vmcnt(5)
; __device__ __forceinline__ unsigned cvt_pk_bf16(float lo, float hi) { unsigned r; asm volatile("v_cvt_pk_bf16_f32 %0, %1, %2" : "=v"(r) : "v"(lo), "v"(hi)); return r; }
; __device__ __forceinline__ float bf_lo(unsigned w) { return __uint_as_float(w << 16); }
; __device__ __forceinline__ float bf_hi(unsigned w) { return __uint_as_float(w & 0xffff0000u); }
; __device__ __forceinline__ void unit(LAS unsigned char* lds, int b, int h, int qb, const bf16_t* Q, const bf16_t* Kn, const bf16_t* Kr, const bf16_t* VT, const bf16_t* proj, bf16_t* ymix, int wv) {
;     ...
;     for (int blk = 0; blk < 4; ++blk)
; #pragma unroll
;         for (int g = 0; g < 4; ++g) { const int dv = 32 * blk + 8 * g + 4 * hi; const u32x2 gt = gts[blk][g];
;             u32x2 w; w.x = cvt_pk_bf16(o[blk][4 * g + 0] * inv * bf_lo(gt.x), o[blk][4 * g + 1] * inv * bf_hi(gt.x)); w.y = cvt_pk_bf16(o[blk][4 * g + 2] * inv * bf_lo(gt.y), o[blk][4 * g + 3] * inv * bf_hi(gt.y));
;             *(u32x2*)(ymix + tok * DM + 512 + h * 128 + dv) = w; }
; __device__ __forceinline__ void phase(LAS unsigned char* lds, const bf16_t* Q, const bf16_t* Kn, const bf16_t* Kr, const bf16_t* VT, const bf16_t* proj, bf16_t* ymix, int vcu, int G, int wv) {
;     for (int n = vcu; n < 1024; n += G) {
	v_permlane32_swap_b32_e32 v188, v190
	v_permlane32_swap_b32_e32 v189, v191
	v_lshlrev_b32_e32 v10, 16, v188
	v_mul_f32_e32 v0, v0, v10
	v_mul_f32_e32 v10, v49, v92
	v_and_b32_e32 v11, 0xffff0000, v188
	v_mul_f32_e32 v10, v10, v11
	v_cvt_pk_bf16_f32 v136, v0, v10
	v_mul_f32_e32 v0, v50, v92
	v_lshlrev_b32_e32 v11, 16, v189
	v_mul_f32_e32 v0, v0, v11
	v_mul_f32_e32 v11, v51, v92
	v_and_b32_e32 v12, 0xffff0000, v189
	v_mul_f32_e32 v11, v11, v12
	v_cvt_pk_bf16_f32 v137, v0, v11
	v_mul_f32_e32 v0, v52, v92
	s_waitcnt vmcnt(5)
	v_lshlrev_b32_e32 v10, 16, v190
	v_mul_f32_e32 v0, v0, v10
	v_mul_f32_e32 v10, v53, v92
	v_and_b32_e32 v11, 0xffff0000, v190
	v_mfma_f32_32x32x16_bf16 v[32:47], v[100:103], v[192:195], v[32:47]
	v_mul_f32_e32 v10, v10, v11
	v_cvt_pk_bf16_f32 v138, v0, v10
	v_mul_f32_e32 v0, v54, v92
	v_lshlrev_b32_e32 v11, 16, v191
	v_mul_f32_e32 v0, v0, v11
	v_mul_f32_e32 v11, v55, v92
	v_and_b32_e32 v12, 0xffff0000, v191
	v_mul_f32_e32 v11, v11, v12
	v_cvt_pk_bf16_f32 v139, v0, v11
	s_nop 1
	v_permlane32_swap_b32_e32 v136, v138
	v_permlane32_swap_b32_e32 v137, v139
	global_store_dwordx4 v[252:253], v[136:139], off offset:1088
	v_mul_f32_e32 v0, v56, v92
	s_waitcnt vmcnt(6)
	v_permlane32_swap_b32_e32 v244, v246
	v_permlane32_swap_b32_e32 v245, v247
	v_lshlrev_b32_e32 v10, 16, v244
	v_mul_f32_e32 v0, v0, v10
	v_mul_f32_e32 v10, v57, v92
	v_and_b32_e32 v11, 0xffff0000, v244
	v_mul_f32_e32 v10, v10, v11
	v_cvt_pk_bf16_f32 v140, v0, v10
	v_mul_f32_e32 v0, v58, v92
	v_lshlrev_b32_e32 v11, 16, v245
	v_mfma_f32_32x32x16_bf16 v[32:47], v[104:107], v[180:183], v[32:47]
	v_mul_f32_e32 v0, v0, v11
	v_mul_f32_e32 v11, v59, v92
	v_and_b32_e32 v12, 0xffff0000, v245
	v_mul_f32_e32 v11, v11, v12
	v_cvt_pk_bf16_f32 v141, v0, v11
	v_mul_f32_e32 v0, v60, v92
	s_waitcnt vmcnt(6)
	v_lshlrev_b32_e32 v10, 16, v246
	v_mul_f32_e32 v0, v0, v10
	v_mul_f32_e32 v10, v61, v92
	v_and_b32_e32 v11, 0xffff0000, v246
	v_mul_f32_e32 v10, v10, v11
	v_cvt_pk_bf16_f32 v142, v0, v10
	v_mul_f32_e32 v0, v62, v92
	v_lshlrev_b32_e32 v11, 16, v247
	v_mul_f32_e32 v0, v0, v11
	v_mul_f32_e32 v11, v63, v92
	v_and_b32_e32 v12, 0xffff0000, v247
	v_mul_f32_e32 v11, v11, v12
	v_cvt_pk_bf16_f32 v143, v0, v11
	s_nop 1
	v_permlane32_swap_b32_e32 v140, v142
	v_permlane32_swap_b32_e32 v141, v143
	global_store_dwordx4 v[252:253], v[140:143], off offset:1120
	v_mul_f32_e32 v0, v32, v92
	s_waitcnt vmcnt(7)
	v_permlane32_swap_b32_e32 v248, v250
	v_permlane32_swap_b32_e32 v249, v251
	v_lshlrev_b32_e32 v10, 16, v248
	v_mul_f32_e32 v0, v0, v10
	v_mul_f32_e32 v10, v33, v92
	v_and_b32_e32 v11, 0xffff0000, v248
	v_mul_f32_e32 v10, v10, v11
	v_cvt_pk_bf16_f32 v136, v0, v10
	v_mul_f32_e32 v0, v34, v92
	v_lshlrev_b32_e32 v11, 16, v249
	v_mul_f32_e32 v0, v0, v11
	v_mul_f32_e32 v11, v35, v92
	v_and_b32_e32 v12, 0xffff0000, v249
	v_mul_f32_e32 v11, v11, v12
	v_cvt_pk_bf16_f32 v137, v0, v11
	v_mul_f32_e32 v0, v36, v92
	s_waitcnt vmcnt(7)
	v_lshlrev_b32_e32 v10, 16, v250
	v_mul_f32_e32 v0, v0, v10
	v_mul_f32_e32 v10, v37, v92
	v_and_b32_e32 v11, 0xffff0000, v250
	v_mfma_f32_32x32x16_bf16 v[16:31], v[112:115], v[192:195], v[16:31]
	v_mul_f32_e32 v10, v10, v11
	v_cvt_pk_bf16_f32 v138, v0, v10
	v_mul_f32_e32 v0, v38, v92
	v_lshlrev_b32_e32 v11, 16, v251
	v_mul_f32_e32 v0, v0, v11
	v_mul_f32_e32 v11, v39, v92
	v_and_b32_e32 v12, 0xffff0000, v251
	v_mul_f32_e32 v11, v11, v12
	v_cvt_pk_bf16_f32 v139, v0, v11
	s_nop 1
	v_permlane32_swap_b32_e32 v136, v138
	v_permlane32_swap_b32_e32 v137, v139
	global_store_dwordx4 v[252:253], v[136:139], off offset:1152
	v_mul_f32_e32 v0, v40, v92
	s_waitcnt vmcnt(7)
	v_permlane32_swap_b32_e32 v156, v158
	v_permlane32_swap_b32_e32 v157, v159
	v_lshlrev_b32_e32 v10, 16, v156
	v_mul_f32_e32 v0, v0, v10
	v_mul_f32_e32 v10, v41, v92
	v_and_b32_e32 v11, 0xffff0000, v156
	v_mul_f32_e32 v10, v10, v11
	v_cvt_pk_bf16_f32 v140, v0, v10
	v_mul_f32_e32 v0, v42, v92
	v_lshlrev_b32_e32 v11, 16, v157
	v_mfma_f32_32x32x16_bf16 v[16:31], v[116:119], v[180:183], v[16:31]
	v_mul_f32_e32 v0, v0, v11
	v_mul_f32_e32 v11, v43, v92
	v_and_b32_e32 v12, 0xffff0000, v157
	v_mul_f32_e32 v11, v11, v12
	v_cvt_pk_bf16_f32 v141, v0, v11
	v_mul_f32_e32 v0, v44, v92
	s_waitcnt vmcnt(7)
	v_lshlrev_b32_e32 v10, 16, v158
	v_mul_f32_e32 v0, v0, v10
	v_mul_f32_e32 v10, v45, v92
	v_and_b32_e32 v11, 0xffff0000, v158
	v_mul_f32_e32 v10, v10, v11
	v_cvt_pk_bf16_f32 v142, v0, v10
	v_mul_f32_e32 v0, v46, v92
	v_lshlrev_b32_e32 v11, 16, v159
	v_mul_f32_e32 v0, v0, v11
	v_mul_f32_e32 v11, v47, v92
	v_and_b32_e32 v12, 0xffff0000, v159
	v_mul_f32_e32 v11, v11, v12
	v_cvt_pk_bf16_f32 v143, v0, v11
	s_nop 1
	v_permlane32_swap_b32_e32 v140, v142
	v_permlane32_swap_b32_e32 v141, v143
	global_store_dwordx4 v[252:253], v[140:143], off offset:1184
	v_mul_f32_e32 v0, v16, v92
	s_waitcnt vmcnt(7)
	v_permlane32_swap_b32_e32 v160, v162
	v_permlane32_swap_b32_e32 v161, v163
	v_lshlrev_b32_e32 v10, 16, v160
	v_mul_f32_e32 v0, v0, v10
	v_mul_f32_e32 v10, v17, v92
	v_and_b32_e32 v11, 0xffff0000, v160
	v_mul_f32_e32 v10, v10, v11
	v_cvt_pk_bf16_f32 v136, v0, v10
	v_mul_f32_e32 v0, v18, v92
	v_lshlrev_b32_e32 v11, 16, v161
	v_mul_f32_e32 v0, v0, v11
	v_mul_f32_e32 v11, v19, v92
	v_and_b32_e32 v12, 0xffff0000, v161
	v_mul_f32_e32 v11, v11, v12
	v_cvt_pk_bf16_f32 v137, v0, v11
	v_mul_f32_e32 v0, v20, v92
	s_waitcnt vmcnt(7)
	v_lshlrev_b32_e32 v10, 16, v162
	v_mul_f32_e32 v0, v0, v10
	v_mul_f32_e32 v10, v21, v92
	v_and_b32_e32 v8, 0xffff0000, v162
	v_mul_f32_e32 v8, v10, v8
	v_cvt_pk_bf16_f32 v138, v0, v8
	v_mul_f32_e32 v0, v22, v92
	v_lshlrev_b32_e32 v10, 16, v163
	v_mul_f32_e32 v0, v0, v10
	v_mul_f32_e32 v10, v23, v92
	v_and_b32_e32 v9, 0xffff0000, v163
	v_mul_f32_e32 v9, v10, v9
	v_cvt_pk_bf16_f32 v139, v0, v9
	s_nop 1
	v_permlane32_swap_b32_e32 v136, v138
	v_permlane32_swap_b32_e32 v137, v139
	global_store_dwordx4 v[252:253], v[136:139], off offset:1216
	v_mul_f32_e32 v0, v24, v92
	s_waitcnt vmcnt(7)
	v_permlane32_swap_b32_e32 v164, v166
	v_permlane32_swap_b32_e32 v165, v167
	v_lshlrev_b32_e32 v8, 16, v164
	v_mul_f32_e32 v0, v0, v8
	v_mul_f32_e32 v8, v25, v92
	v_and_b32_e32 v4, 0xffff0000, v164
	v_mul_f32_e32 v4, v8, v4
	v_cvt_pk_bf16_f32 v140, v0, v4
	v_mul_f32_e32 v0, v26, v92
	v_lshlrev_b32_e32 v8, 16, v165
	v_mul_f32_e32 v0, v0, v8
	v_mul_f32_e32 v8, v27, v92
	v_and_b32_e32 v5, 0xffff0000, v165
	v_mul_f32_e32 v5, v8, v5
	v_cvt_pk_bf16_f32 v141, v0, v5
	v_mul_f32_e32 v0, v28, v92
	s_waitcnt vmcnt(7)
	v_lshlrev_b32_e32 v4, 16, v166
	v_mul_f32_e32 v0, v0, v4
	v_mul_f32_e32 v4, v29, v92
	v_and_b32_e32 v2, 0xffff0000, v166
	v_mul_f32_e32 v2, v4, v2
	v_cvt_pk_bf16_f32 v142, v0, v2
	v_mul_f32_e32 v0, v30, v92
	v_lshlrev_b32_e32 v4, 16, v167
	v_mul_f32_e32 v0, v0, v4
	v_mul_f32_e32 v4, v31, v92
	v_and_b32_e32 v3, 0xffff0000, v167
	v_mul_f32_e32 v3, v4, v3
	v_cvt_pk_bf16_f32 v143, v0, v3
	s_nop 1
	v_permlane32_swap_b32_e32 v140, v142
	v_permlane32_swap_b32_e32 v141, v143
	global_store_dwordx4 v[252:253], v[140:143], off offset:1248
	s_cbranch_scc0 .LBB0_633

; __device__ __forceinline__ void unit(LAS unsigned char* lds, int b, int h, int qb, const bf16_t* Q, const bf16_t* Kn, const bf16_t* Kr, const bf16_t* VT, const bf16_t* proj, bf16_t* ymix, int wv) {
;     ...
;     const size_t tok = (size_t)tok0 + qidx;
;     u32x2 gts[4][4];
; #pragma unroll
;     for (int blk = 0; blk < 4; ++blk)
; #pragma unroll
;         for (int g = 0; g < 4; ++g) gts[blk][g] = *(const u32x2*)(proj + tok * NIN + PJ_BG + h * 128 + 32 * blk + 8 * g + 4 * hi);
.Leg_a:
	v_add_u32_e32 v176, s54, v216
	v_mov_b32_e32 v252, s22
	v_mov_b32_e32 v253, s23
	v_mad_u64_u32 v[252:253], vcc, v176, s66, v[252:253]
	v_lshlrev_b32_e32 v176, 2, v225
	v_lshl_add_u32 v176, s69, 1, v176
	v_add_u32_e32 v176, 0x1000, v176
	v_mov_b32_e32 v177, 0
	v_lshl_add_u64 v[252:253], v[252:253], 0, v[176:177]
	global_load_dwordx4 v[176:179], v[252:253], off
	global_load_dwordx4 v[184:187], v[252:253], off offset:32
	global_load_dwordx4 v[188:191], v[252:253], off offset:64
	global_load_dwordx4 v[244:247], v[252:253], off offset:96
	global_load_dwordx4 v[248:251], v[252:253], off offset:128
	s_branch .LBB0_624

; __device__ __forceinline__ unsigned cvt_pk_bf16(float lo, float hi) { unsigned r; asm volatile("v_cvt_pk_bf16_f32 %0, %1, %2" : "=v"(r) : "v"(lo), "v"(hi)); return r; }
; __device__ __forceinline__ float bf_lo(unsigned w) { return __uint_as_float(w << 16); }
; __device__ __forceinline__ float bf_hi(unsigned w) { return __uint_as_float(w & 0xffff0000u); }
; __device__ __forceinline__ void unit(LAS unsigned char* lds, int b, int h, int qb, const bf16_t* Q, const bf16_t* Kn, const bf16_t* Kr, const bf16_t* VT, const bf16_t* proj, bf16_t* ymix, int wv) {
;     ...
;     lrun += shfl_xor_f(lrun, 32);
;     const float inv = 1.f / lrun;
;     const size_t tok = (size_t)tok0 + qidx;
;     u32x2 gts[4][4];
; #pragma unroll
;     for (int blk = 0; blk < 4; ++blk)
; #pragma unroll
;         for (int g = 0; g < 4; ++g) gts[blk][g] = *(const u32x2*)(proj + tok * NIN + PJ_BG + h * 128 + 32 * blk + 8 * g + 4 * hi);
; #pragma unroll
;     for (int blk = 0; blk < 4; ++blk)
; #pragma unroll
;         for (int g = 0; g < 4; ++g) { const int dv = 32 * blk + 8 * g + 4 * hi; const u32x2 gt = gts[blk][g];
;             u32x2 w; w.x = cvt_pk_bf16(o[blk][4 * g + 0] * inv * bf_lo(gt.x), o[blk][4 * g + 1] * inv * bf_hi(gt.x)); w.y = cvt_pk_bf16(o[blk][4 * g + 2] * inv * bf_lo(gt.y), o[blk][4 * g + 3] * inv * bf_hi(gt.y));
;             *(u32x2*)(ymix + tok * DM + 512 + h * 128 + dv) = w; }
.LBB0_1170:
	s_add_i32 s6, s58, 0
	s_add_i32 s6, s6, 0x12c00
	v_add3_u32 v0, s6, v227, v226
	ds_read2_b64 v[2:5], v0 offset1:2
	v_ashrrev_i32_e32 v217, 31, v216
	v_mov_b64_e32 v[6:7], s[46:47]
	v_lshl_add_u64 v[120:121], v[216:217], 0, s[16:17]
	v_mad_u64_u32 v[122:123], s[16:17], v120, s54, v[6:7]
	ds_read2_b64 v[6:9], v0 offset0:4 offset1:6
	ds_read2_b64 v[12:15], v0 offset0:8 offset1:10
	v_add_u32_e32 v88, 0x1000, v0
	v_add_u32_e32 v104, 0x2000, v0
	s_waitcnt lgkmcnt(2)
	v_mfma_f32_32x32x16_bf16 v[64:79], v[2:5], v[200:203], v[64:79]
	ds_read2_b64 v[2:5], v0 offset0:12 offset1:14
	v_add_u32_e32 v0, 0x3000, v0
	v_mad_i32_i24 v123, v121, s54, v123
	s_lshl_b32 s6, s56, 1
	ds_read2_b64 v[80:83], v88 offset0:32 offset1:34
	ds_read2_b64 v[84:87], v88 offset0:36 offset1:38
	v_mov_b32_e32 v11, v222
	s_add_i32 s3, s3, s31
	s_waitcnt lgkmcnt(4)
	v_mfma_f32_32x32x16_bf16 v[64:79], v[6:9], v[196:199], v[64:79]
	ds_read2_b64 v[6:9], v88 offset0:40 offset1:42
	ds_read2_b64 v[88:91], v88 offset0:44 offset1:46
	ds_read2_b64 v[92:95], v104 offset0:64 offset1:66
	ds_read2_b64 v[96:99], v104 offset0:68 offset1:70
	ds_read2_b64 v[100:103], v104 offset0:72 offset1:74
	ds_read2_b64 v[104:107], v104 offset0:76 offset1:78
	ds_read2_b64 v[108:111], v0 offset0:96 offset1:98
	s_cmpk_lt_i32 s3, 0x400
	s_waitcnt lgkmcnt(10)
	v_mfma_f32_32x32x16_bf16 v[64:79], v[12:15], v[192:195], v[64:79]
	ds_read2_b64 v[12:15], v0 offset0:100 offset1:102
	ds_read2_b64 v[112:115], v0 offset0:104 offset1:106
	ds_read2_b64 v[116:119], v0 offset0:108 offset1:110
	v_lshlrev_b32_e32 v0, 1, v225
	s_waitcnt lgkmcnt(0)
	s_barrier
	v_mfma_f32_32x32x16_bf16 v[64:79], v[2:5], v[188:191], v[64:79]
	v_lshl_add_u64 v[2:3], v[122:123], 0, s[6:7]
	v_lshl_add_u64 v[2:3], v[2:3], 0, v[0:1]
	v_add_co_u32_e32 v4, vcc, s55, v2
	s_nop 1
	v_addc_co_u32_e32 v5, vcc, 0, v3, vcc
	v_and_b32_e32 v168, 32, v222
	v_lshrrev_b32_e32 v168, 2, v168
	v_mov_b32_e32 v169, 0
	v_lshl_add_u64 v[168:169], v[4:5], 0, v[168:169]
	v_lshl_add_u64 v[2:3], v[2:3], 0, s[10:11]
	v_mfma_f32_32x32x16_bf16 v[48:63], v[80:83], v[200:203], v[48:63]
	v_lshlrev_b32_e32 v4, 2, v11
	v_xor_b32_e32 v4, 0x80, v4
	ds_bpermute_b32 v4, v4, v10
	v_mfma_f32_32x32x16_bf16 v[48:63], v[84:87], v[196:199], v[48:63]
	v_mfma_f32_32x32x16_bf16 v[48:63], v[6:9], v[192:195], v[48:63]
	s_waitcnt lgkmcnt(0)
	v_add_f32_e32 v6, v10, v4
	v_div_scale_f32 v7, s[16:17], v6, v6, 1.0
	v_rcp_f32_e32 v134, v7
	v_mfma_f32_32x32x16_bf16 v[48:63], v[88:91], v[188:191], v[48:63]
	global_load_dwordx4 v[156:159], v[168:169], off offset:160
	global_load_dwordx4 v[160:163], v[168:169], off offset:192
	global_load_dwordx4 v[164:167], v[168:169], off offset:224
	s_nop 0
	v_mfma_f32_32x32x16_bf16 v[32:47], v[92:95], v[200:203], v[32:47]
	v_fma_f32 v92, -v7, v134, 1.0
	v_fmac_f32_e32 v134, v92, v134
	v_div_scale_f32 v92, vcc, 1.0, v6, 1.0
	v_mul_f32_e32 v93, v92, v134
	v_fma_f32 v94, -v7, v93, v92
	v_fmac_f32_e32 v93, v94, v134
	v_fma_f32 v7, -v7, v93, v92
	v_mfma_f32_32x32x16_bf16 v[16:31], v[108:111], v[200:203], v[16:31]
	v_div_fmas_f32 v7, v7, v134, v93
	v_div_fixup_f32 v92, v7, v6, 1.0
	v_mul_f32_e32 v64, v64, v92
	v_lshlrev_b64 v[6:7], 12, v[120:121]
	v_mul_f32_e32 v65, v65, v92
	v_lshl_add_u64 v[6:7], s[22:23], 0, v[6:7]
	v_lshl_add_u64 v[6:7], v[6:7], 0, s[6:7]
	v_lshl_add_u64 v[6:7], v[6:7], 0, v[0:1]
	v_mul_f32_e32 v0, v68, v92
	v_mfma_f32_32x32x16_bf16 v[16:31], v[12:15], v[196:199], v[16:31]
	v_mul_f32_e32 v12, v69, v92
	s_waitcnt vmcnt(3)
	v_permlane32_swap_b32_e32 v176, v178
	v_permlane32_swap_b32_e32 v177, v179
	v_lshlrev_b32_e32 v93, 16, v176
	v_mul_f32_e32 v64, v64, v93
	v_and_b32_e32 v93, 0xffff0000, v176
	v_mul_f32_e32 v65, v65, v93
	v_cvt_pk_bf16_f32 v136, v64, v65
	v_mul_f32_e32 v65, v66, v92
	v_lshlrev_b32_e32 v66, 16, v177
	v_mul_f32_e32 v65, v65, v66
	v_mul_f32_e32 v66, v67, v92
	v_and_b32_e32 v67, 0xffff0000, v177
	v_mul_f32_e32 v66, v66, v67
	v_cvt_pk_bf16_f32 v137, v65, v66
	v_and_b32_e32 v252, 32, v222
	v_lshrrev_b32_e32 v252, 2, v252
	v_mov_b32_e32 v253, 0
	v_lshl_add_u64 v[252:253], v[6:7], 0, v[252:253]
	s_waitcnt vmcnt(3)
	v_lshlrev_b32_e32 v64, 16, v178
	v_and_b32_e32 v13, 0xffff0000, v178
	v_mul_f32_e32 v0, v0, v64
	v_mul_f32_e32 v12, v12, v13
	v_cvt_pk_bf16_f32 v138, v0, v12
	v_mul_f32_e32 v0, v70, v92
	v_lshlrev_b32_e32 v13, 16, v179
	v_mul_f32_e32 v0, v0, v13
	v_mul_f32_e32 v13, v71, v92
	v_and_b32_e32 v14, 0xffff0000, v179
	v_mul_f32_e32 v13, v13, v14
	v_cvt_pk_bf16_f32 v139, v0, v13
	s_nop 1
	v_permlane32_swap_b32_e32 v136, v138
	v_permlane32_swap_b32_e32 v137, v139
	global_store_dwordx4 v[252:253], v[136:139], off offset:1024
	v_mul_f32_e32 v0, v72, v92
	s_waitcnt vmcnt(4)
	v_permlane32_swap_b32_e32 v180, v182
	v_permlane32_swap_b32_e32 v181, v183
	v_lshlrev_b32_e32 v12, 16, v180
	v_mul_f32_e32 v0, v0, v12
	v_mul_f32_e32 v12, v73, v92
	v_and_b32_e32 v13, 0xffff0000, v180
	v_mul_f32_e32 v12, v12, v13
	v_cvt_pk_bf16_f32 v140, v0, v12
	v_mul_f32_e32 v0, v74, v92
	v_lshlrev_b32_e32 v13, 16, v181
	v_mul_f32_e32 v0, v0, v13
	v_mul_f32_e32 v13, v75, v92
	v_and_b32_e32 v14, 0xffff0000, v181
	v_mul_f32_e32 v13, v13, v14
	v_cvt_pk_bf16_f32 v141, v0, v13
	v_mul_f32_e32 v0, v76, v92
	s_waitcnt vmcnt(4)
	v_lshlrev_b32_e32 v12, 16, v182
	v_mul_f32_e32 v0, v0, v12
	v_mul_f32_e32 v12, v77, v92
	v_and_b32_e32 v10, 0xffff0000, v182
	v_mul_f32_e32 v10, v12, v10
	v_cvt_pk_bf16_f32 v142, v0, v10
	v_mul_f32_e32 v0, v78, v92
	v_lshlrev_b32_e32 v12, 16, v183
	v_mul_f32_e32 v0, v0, v12
	v_mul_f32_e32 v12, v79, v92
	v_and_b32_e32 v11, 0xffff0000, v183
	v_mul_f32_e32 v11, v12, v11
	v_mfma_f32_32x32x16_bf16 v[32:47], v[96:99], v[196:199], v[32:47]
	v_cvt_pk_bf16_f32 v143, v0, v11
	s_nop 1
	v_permlane32_swap_b32_e32 v140, v142
	v_permlane32_swap_b32_e32 v141, v143
	global_store_dwordx4 v[252:253], v[140:143], off offset:1056
	v_mul_f32_e32 v0, v48, v92
	s_waitcnt vmcnt(5)
; __device__ __forceinline__ unsigned cvt_pk_bf16(float lo, float hi) { unsigned r; asm volatile("v_cvt_pk_bf16_f32 %0, %1, %2" : "=v"(r) : "v"(lo), "v"(hi)); return r; }
; __device__ __forceinline__ float bf_lo(unsigned w) { return __uint_as_float(w << 16); }
; __device__ __forceinline__ float bf_hi(unsigned w) { return __uint_as_float(w & 0xffff0000u); }
; __device__ __forceinline__ void unit(LAS unsigned char* lds, int b, int h, int qb, const bf16_t* Q, const bf16_t* Kn, const bf16_t* Kr, const bf16_t* VT, const bf16_t* proj, bf16_t* ymix, int wv) {
;     ...
;     for (int blk = 0; blk < 4; ++blk)
; #pragma unroll
;         for (int g = 0; g < 4; ++g) { const int dv = 32 * blk + 8 * g + 4 * hi; const u32x2 gt = gts[blk][g];
;             u32x2 w; w.x = cvt_pk_bf16(o[blk][4 * g + 0] * inv * bf_lo(gt.x), o[blk][4 * g + 1] * inv * bf_hi(gt.x)); w.y = cvt_pk_bf16(o[blk][4 * g + 2] * inv * bf_lo(gt.y), o[blk][4 * g + 3] * inv * bf_hi(gt.y));
;             *(u32x2*)(ymix + tok * DM + 512 + h * 128 + dv) = w; }
; __device__ __forceinline__ void phase(LAS unsigned char* lds, const bf16_t* Q, const bf16_t* Kn, const bf16_t* Kr, const bf16_t* VT, const bf16_t* proj, bf16_t* ymix, int vcu, int G, int wv) {
;     for (int n = vcu; n < 1024; n += G) {
	v_permlane32_swap_b32_e32 v184, v186
	v_permlane32_swap_b32_e32 v185, v187
	v_lshlrev_b32_e32 v10, 16, v184
	v_mul_f32_e32 v0, v0, v10
	v_mul_f32_e32 v10, v49, v92
	v_and_b32_e32 v11, 0xffff0000, v184
	v_mul_f32_e32 v10, v10, v11
	v_cvt_pk_bf16_f32 v136, v0, v10
	v_mul_f32_e32 v0, v50, v92
	v_lshlrev_b32_e32 v11, 16, v185
	v_mul_f32_e32 v0, v0, v11
	v_mul_f32_e32 v11, v51, v92
	v_and_b32_e32 v12, 0xffff0000, v185
	v_mul_f32_e32 v11, v11, v12
	v_cvt_pk_bf16_f32 v137, v0, v11
	v_mul_f32_e32 v0, v52, v92
	s_waitcnt vmcnt(5)
	v_lshlrev_b32_e32 v10, 16, v186
	v_mul_f32_e32 v0, v0, v10
	v_mul_f32_e32 v10, v53, v92
	v_and_b32_e32 v11, 0xffff0000, v186
	v_mfma_f32_32x32x16_bf16 v[32:47], v[100:103], v[192:195], v[32:47]
	v_mul_f32_e32 v10, v10, v11
	v_cvt_pk_bf16_f32 v138, v0, v10
	v_mul_f32_e32 v0, v54, v92
	v_lshlrev_b32_e32 v11, 16, v187
	v_mul_f32_e32 v0, v0, v11
	v_mul_f32_e32 v11, v55, v92
	v_and_b32_e32 v12, 0xffff0000, v187
	v_mul_f32_e32 v11, v11, v12
	v_cvt_pk_bf16_f32 v139, v0, v11
	s_nop 1
	v_permlane32_swap_b32_e32 v136, v138
	v_permlane32_swap_b32_e32 v137, v139
	global_store_dwordx4 v[252:253], v[136:139], off offset:1088
	v_mul_f32_e32 v0, v56, v92
	s_waitcnt vmcnt(6)
	v_permlane32_swap_b32_e32 v244, v246
	v_permlane32_swap_b32_e32 v245, v247
	v_lshlrev_b32_e32 v10, 16, v244
	v_mul_f32_e32 v0, v0, v10
	v_mul_f32_e32 v10, v57, v92
	v_and_b32_e32 v11, 0xffff0000, v244
	v_mul_f32_e32 v10, v10, v11
	v_cvt_pk_bf16_f32 v140, v0, v10
	v_mul_f32_e32 v0, v58, v92
	v_lshlrev_b32_e32 v11, 16, v245
	v_mfma_f32_32x32x16_bf16 v[32:47], v[104:107], v[188:191], v[32:47]
	v_mul_f32_e32 v0, v0, v11
	v_mul_f32_e32 v11, v59, v92
	v_and_b32_e32 v12, 0xffff0000, v245
	v_mul_f32_e32 v11, v11, v12
	v_cvt_pk_bf16_f32 v141, v0, v11
	v_mul_f32_e32 v0, v60, v92
	s_waitcnt vmcnt(6)
	v_lshlrev_b32_e32 v10, 16, v246
	v_mul_f32_e32 v0, v0, v10
	v_mul_f32_e32 v10, v61, v92
	v_and_b32_e32 v11, 0xffff0000, v246
	v_mul_f32_e32 v10, v10, v11
	v_cvt_pk_bf16_f32 v142, v0, v10
	v_mul_f32_e32 v0, v62, v92
	v_lshlrev_b32_e32 v11, 16, v247
	v_mul_f32_e32 v0, v0, v11
	v_mul_f32_e32 v11, v63, v92
	v_and_b32_e32 v12, 0xffff0000, v247
	v_mul_f32_e32 v11, v11, v12
	v_cvt_pk_bf16_f32 v143, v0, v11
	s_nop 1
	v_permlane32_swap_b32_e32 v140, v142
	v_permlane32_swap_b32_e32 v141, v143
	global_store_dwordx4 v[252:253], v[140:143], off offset:1120
	v_mul_f32_e32 v0, v32, v92
	s_waitcnt vmcnt(7)
	v_permlane32_swap_b32_e32 v248, v250
	v_permlane32_swap_b32_e32 v249, v251
	v_lshlrev_b32_e32 v10, 16, v248
	v_mul_f32_e32 v0, v0, v10
	v_mul_f32_e32 v10, v33, v92
	v_and_b32_e32 v11, 0xffff0000, v248
	v_mul_f32_e32 v10, v10, v11
	v_cvt_pk_bf16_f32 v136, v0, v10
	v_mul_f32_e32 v0, v34, v92
	v_lshlrev_b32_e32 v11, 16, v249
	v_mul_f32_e32 v0, v0, v11
	v_mul_f32_e32 v11, v35, v92
	v_and_b32_e32 v12, 0xffff0000, v249
	v_mul_f32_e32 v11, v11, v12
	v_cvt_pk_bf16_f32 v137, v0, v11
	v_mul_f32_e32 v0, v36, v92
	s_waitcnt vmcnt(7)
	v_lshlrev_b32_e32 v10, 16, v250
	v_mul_f32_e32 v0, v0, v10
	v_mul_f32_e32 v10, v37, v92
	v_and_b32_e32 v11, 0xffff0000, v250
	v_mfma_f32_32x32x16_bf16 v[16:31], v[112:115], v[192:195], v[16:31]
	v_mul_f32_e32 v10, v10, v11
	v_cvt_pk_bf16_f32 v138, v0, v10
	v_mul_f32_e32 v0, v38, v92
	v_lshlrev_b32_e32 v11, 16, v251
	v_mul_f32_e32 v0, v0, v11
	v_mul_f32_e32 v11, v39, v92
	v_and_b32_e32 v12, 0xffff0000, v251
	v_mul_f32_e32 v11, v11, v12
	v_cvt_pk_bf16_f32 v139, v0, v11
	s_nop 1
	v_permlane32_swap_b32_e32 v136, v138
	v_permlane32_swap_b32_e32 v137, v139
	global_store_dwordx4 v[252:253], v[136:139], off offset:1152
	v_mul_f32_e32 v0, v40, v92
	s_waitcnt vmcnt(7)
	v_permlane32_swap_b32_e32 v156, v158
	v_permlane32_swap_b32_e32 v157, v159
	v_lshlrev_b32_e32 v10, 16, v156
	v_mul_f32_e32 v0, v0, v10
	v_mul_f32_e32 v10, v41, v92
	v_and_b32_e32 v11, 0xffff0000, v156
	v_mul_f32_e32 v10, v10, v11
	v_cvt_pk_bf16_f32 v140, v0, v10
	v_mul_f32_e32 v0, v42, v92
	v_lshlrev_b32_e32 v11, 16, v157
	v_mfma_f32_32x32x16_bf16 v[16:31], v[116:119], v[188:191], v[16:31]
	v_mul_f32_e32 v0, v0, v11
	v_mul_f32_e32 v11, v43, v92
	v_and_b32_e32 v12, 0xffff0000, v157
	v_mul_f32_e32 v11, v11, v12
	v_cvt_pk_bf16_f32 v141, v0, v11
	v_mul_f32_e32 v0, v44, v92
	s_waitcnt vmcnt(7)
	v_lshlrev_b32_e32 v10, 16, v158
	v_mul_f32_e32 v0, v0, v10
	v_mul_f32_e32 v10, v45, v92
	v_and_b32_e32 v11, 0xffff0000, v158
	v_mul_f32_e32 v10, v10, v11
	v_cvt_pk_bf16_f32 v142, v0, v10
	v_mul_f32_e32 v0, v46, v92
	v_lshlrev_b32_e32 v11, 16, v159
	v_mul_f32_e32 v0, v0, v11
	v_mul_f32_e32 v11, v47, v92
	v_and_b32_e32 v12, 0xffff0000, v159
	v_mul_f32_e32 v11, v11, v12
	v_cvt_pk_bf16_f32 v143, v0, v11
	s_nop 1
	v_permlane32_swap_b32_e32 v140, v142
	v_permlane32_swap_b32_e32 v141, v143
	global_store_dwordx4 v[252:253], v[140:143], off offset:1184
	v_mul_f32_e32 v0, v16, v92
	s_waitcnt vmcnt(7)
	v_permlane32_swap_b32_e32 v160, v162
	v_permlane32_swap_b32_e32 v161, v163
	v_lshlrev_b32_e32 v10, 16, v160
	v_mul_f32_e32 v0, v0, v10
	v_mul_f32_e32 v10, v17, v92
	v_and_b32_e32 v11, 0xffff0000, v160
	v_mul_f32_e32 v10, v10, v11
	v_cvt_pk_bf16_f32 v136, v0, v10
	v_mul_f32_e32 v0, v18, v92
	v_lshlrev_b32_e32 v11, 16, v161
	v_mul_f32_e32 v0, v0, v11
	v_mul_f32_e32 v11, v19, v92
	v_and_b32_e32 v12, 0xffff0000, v161
	v_mul_f32_e32 v11, v11, v12
	v_cvt_pk_bf16_f32 v137, v0, v11
	v_mul_f32_e32 v0, v20, v92
	s_waitcnt vmcnt(7)
	v_lshlrev_b32_e32 v10, 16, v162
	v_mul_f32_e32 v0, v0, v10
	v_mul_f32_e32 v10, v21, v92
	v_and_b32_e32 v8, 0xffff0000, v162
	v_mul_f32_e32 v8, v10, v8
	v_cvt_pk_bf16_f32 v138, v0, v8
	v_mul_f32_e32 v0, v22, v92
	v_lshlrev_b32_e32 v10, 16, v163
	v_mul_f32_e32 v0, v0, v10
	v_mul_f32_e32 v10, v23, v92
	v_and_b32_e32 v9, 0xffff0000, v163
	v_mul_f32_e32 v9, v10, v9
	v_cvt_pk_bf16_f32 v139, v0, v9
	s_nop 1
	v_permlane32_swap_b32_e32 v136, v138
	v_permlane32_swap_b32_e32 v137, v139
	global_store_dwordx4 v[252:253], v[136:139], off offset:1216
	v_mul_f32_e32 v0, v24, v92
	s_waitcnt vmcnt(7)
	v_permlane32_swap_b32_e32 v164, v166
	v_permlane32_swap_b32_e32 v165, v167
	v_lshlrev_b32_e32 v8, 16, v164
	v_mul_f32_e32 v0, v0, v8
	v_mul_f32_e32 v8, v25, v92
	v_and_b32_e32 v4, 0xffff0000, v164
	v_mul_f32_e32 v4, v8, v4
	v_cvt_pk_bf16_f32 v140, v0, v4
	v_mul_f32_e32 v0, v26, v92
	v_lshlrev_b32_e32 v8, 16, v165
	v_mul_f32_e32 v0, v0, v8
	v_mul_f32_e32 v8, v27, v92
	v_and_b32_e32 v5, 0xffff0000, v165
	v_mul_f32_e32 v5, v8, v5
	v_cvt_pk_bf16_f32 v141, v0, v5
	v_mul_f32_e32 v0, v28, v92
	s_waitcnt vmcnt(7)
	v_lshlrev_b32_e32 v4, 16, v166
	v_mul_f32_e32 v0, v0, v4
	v_mul_f32_e32 v4, v29, v92
	v_and_b32_e32 v2, 0xffff0000, v166
	v_mul_f32_e32 v2, v4, v2
	v_cvt_pk_bf16_f32 v142, v0, v2
	v_mul_f32_e32 v0, v30, v92
	v_lshlrev_b32_e32 v4, 16, v167
	v_mul_f32_e32 v0, v0, v4
	v_mul_f32_e32 v4, v31, v92
	v_and_b32_e32 v3, 0xffff0000, v167
	v_mul_f32_e32 v3, v4, v3
	v_cvt_pk_bf16_f32 v143, v0, v3
	s_nop 1
	v_permlane32_swap_b32_e32 v140, v142
	v_permlane32_swap_b32_e32 v141, v143
	global_store_dwordx4 v[252:253], v[140:143], off offset:1248
	s_cbranch_scc0 .LBB0_1198

; __device__ __forceinline__ void unit(LAS unsigned char* lds, int b, int h, int qb, const bf16_t* Q, const bf16_t* Kn, const bf16_t* Kr, const bf16_t* VT, const bf16_t* proj, bf16_t* ymix, int wv) {
;     ...
;     const size_t tok = (size_t)tok0 + qidx;
;     u32x2 gts[4][4];
; #pragma unroll
;     for (int blk = 0; blk < 4; ++blk)
; #pragma unroll
;         for (int g = 0; g < 4; ++g) gts[blk][g] = *(const u32x2*)(proj + tok * NIN + PJ_BG + h * 128 + 32 * blk + 8 * g + 4 * hi);
.Leg_b:
	v_add_u32_e32 v176, s16, v216
	v_mov_b32_e32 v252, s46
	v_mov_b32_e32 v253, s47
	v_mad_u64_u32 v[252:253], vcc, v176, s54, v[252:253]
	v_lshlrev_b32_e32 v176, 2, v225
	v_lshl_add_u32 v176, s56, 1, v176
	v_add_u32_e32 v176, 0x1000, v176
	v_mov_b32_e32 v177, 0
	v_lshl_add_u64 v[252:253], v[252:253], 0, v[176:177]
	global_load_dwordx4 v[176:179], v[252:253], off
	global_load_dwordx4 v[180:183], v[252:253], off offset:32
	global_load_dwordx4 v[184:187], v[252:253], off offset:64
	global_load_dwordx4 v[244:247], v[252:253], off offset:96
	global_load_dwordx4 v[248:251], v[252:253], off offset:128
	s_branch .LBB0_1189
